# even in-proj epilogue, dt tile path: eight row-statistic loads issued together with counted waits
# speedup vs baseline: 1.0076x; 1.0027x over previous
.LBB0_684:
	v_lshlrev_b32_e32 v74, 2, v197
	v_ashrrev_i32_e32 v195, 31, v194
	v_ashrrev_i32_e32 v75, 31, v74
	v_lshlrev_b64 v[76:77], 6, v[194:195]
	v_lshl_add_u64 v[78:79], s[68:69], 0, v[76:77]
	v_lshlrev_b64 v[76:77], 2, v[74:75]
	v_lshl_add_u64 v[74:75], v[78:79], 0, v[76:77]
	global_load_dwordx4 v[66:69], v[198:199], off offset:16
	global_load_dwordx4 v[70:73], v[198:199], off
	global_load_dwordx4 v[78:81], v[74:75], off
	global_load_dwordx4 v[104:107], v[74:75], off offset:1024
	global_load_dwordx4 v[108:111], v[74:75], off offset:2048
	global_load_dwordx4 v[112:115], v[74:75], off offset:3072
	s_mov_b64 s[98:99], 0x2000
	v_lshl_add_u64 v[116:117], v[74:75], 0, s[98:99]
	global_load_dwordx4 v[120:123], v[116:117], off
	global_load_dwordx4 v[124:127], v[116:117], off offset:1024
	global_load_dwordx4 v[128:131], v[116:117], off offset:2048
	global_load_dwordx4 v[132:135], v[116:117], off offset:3072
	v_ashrrev_i32_e32 v197, 31, v196
	s_waitcnt vmcnt(7)
	v_add_f32_e32 v74, v78, v79
	v_add_f32_e32 v75, v80, v81
	v_add_f32_e32 v74, v74, v75
	v_mov_b32_e32 v75, v74
	s_nop 1
	v_permlane16_swap_b32_e32 v74, v75
	v_add_f32_e32 v74, v74, v75
	v_mov_b32_e32 v75, v74
	s_nop 1
	v_permlane32_swap_b32_e32 v74, v75
	v_add_f32_e32 v74, v74, v75
	v_fmamk_f32 v74, v74, 0x3a800000, v178
	v_cmp_gt_f32_e32 vcc, s84, v74
	v_mul_f32_e32 v75, 0x4b800000, v74
	s_nop 0
	v_cndmask_b32_e32 v74, v74, v75, vcc
	v_rsq_f32_e32 v74, v74
	s_nop 0
	v_mul_f32_e32 v75, 0x45800000, v74
	v_cndmask_b32_e32 v78, v74, v75, vcc
	v_lshlrev_b64 v[74:75], 7, v[194:195]
	v_lshl_add_u64 v[80:81], s[56:57], 0, v[74:75]
	v_lshlrev_b64 v[74:75], 2, v[196:197]
	v_lshl_add_u64 v[80:81], v[80:81], 0, v[74:75]
	v_pk_fma_f32 v[64:65], v[64:65], v[78:79], v[72:73] op_sel_hi:[1,0,1]
	v_pk_fma_f32 v[62:63], v[62:63], v[78:79], v[70:71] op_sel_hi:[1,0,1]
	global_store_dwordx4 v[80:81], v[62:65], off
	v_pk_fma_f32 v[60:61], v[60:61], v[78:79], v[68:69] op_sel_hi:[1,0,1]
	v_pk_fma_f32 v[58:59], v[58:59], v[78:79], v[66:67] op_sel_hi:[1,0,1]
	v_add_u32_e32 v62, 16, v194
	v_ashrrev_i32_e32 v63, 31, v62
	global_store_dwordx4 v[80:81], v[58:61], off offset:16
	s_nop 1
	v_lshlrev_b64 v[58:59], 6, v[62:63]
	v_lshl_add_u64 v[58:59], s[68:69], 0, v[58:59]
	v_lshl_add_u64 v[58:59], v[58:59], 0, v[76:77]
	s_waitcnt vmcnt(8)
	v_mov_b32_e32 v58, v104
	v_mov_b32_e32 v59, v105
	v_mov_b32_e32 v60, v106
	v_mov_b32_e32 v61, v107
	v_add_f32_e32 v58, v58, v59
	v_add_f32_e32 v59, v60, v61
	v_add_f32_e32 v58, v58, v59
	v_mov_b32_e32 v59, v58
	s_nop 1
	v_permlane16_swap_b32_e32 v58, v59
	v_add_f32_e32 v58, v58, v59
	v_mov_b32_e32 v59, v58
	s_nop 1
	v_permlane32_swap_b32_e32 v58, v59
	v_add_f32_e32 v58, v58, v59
	v_fmamk_f32 v58, v58, 0x3a800000, v178
	v_cmp_gt_f32_e32 vcc, s84, v58
	v_mul_f32_e32 v59, 0x4b800000, v58
	v_lshlrev_b64 v[60:61], 7, v[62:63]
	v_cndmask_b32_e32 v58, v58, v59, vcc
	v_rsq_f32_e32 v58, v58
	v_lshl_add_u64 v[60:61], s[56:57], 0, v[60:61]
	v_lshl_add_u64 v[60:61], v[60:61], 0, v[74:75]
	v_mul_f32_e32 v59, 0x45800000, v58
	v_cndmask_b32_e32 v58, v58, v59, vcc
	v_pk_fma_f32 v[56:57], v[56:57], v[58:59], v[72:73] op_sel_hi:[1,0,1]
	v_pk_fma_f32 v[54:55], v[54:55], v[58:59], v[70:71] op_sel_hi:[1,0,1]
	global_store_dwordx4 v[60:61], v[54:57], off
	v_pk_fma_f32 v[52:53], v[52:53], v[58:59], v[68:69] op_sel_hi:[1,0,1]
	v_pk_fma_f32 v[50:51], v[50:51], v[58:59], v[66:67] op_sel_hi:[1,0,1]
	v_add_u32_e32 v54, 32, v194
	v_ashrrev_i32_e32 v55, 31, v54
	global_store_dwordx4 v[60:61], v[50:53], off offset:16
	s_nop 1
	v_lshlrev_b64 v[50:51], 6, v[54:55]
	v_lshl_add_u64 v[50:51], s[68:69], 0, v[50:51]
	v_lshl_add_u64 v[50:51], v[50:51], 0, v[76:77]
	s_waitcnt vmcnt(9)
	v_mov_b32_e32 v50, v108
	v_mov_b32_e32 v51, v109
	v_mov_b32_e32 v52, v110
	v_mov_b32_e32 v53, v111
	v_add_f32_e32 v50, v50, v51
	v_add_f32_e32 v51, v52, v53
	v_add_f32_e32 v50, v50, v51
	v_mov_b32_e32 v51, v50
	s_nop 1
	v_permlane16_swap_b32_e32 v50, v51
	v_add_f32_e32 v50, v50, v51
	v_mov_b32_e32 v51, v50
	s_nop 1
	v_permlane32_swap_b32_e32 v50, v51
	v_add_f32_e32 v50, v50, v51
	v_fmamk_f32 v50, v50, 0x3a800000, v178
	v_cmp_gt_f32_e32 vcc, s84, v50
	v_mul_f32_e32 v51, 0x4b800000, v50
	v_lshlrev_b64 v[52:53], 7, v[54:55]
	v_cndmask_b32_e32 v50, v50, v51, vcc
	v_rsq_f32_e32 v50, v50
	v_lshl_add_u64 v[52:53], s[56:57], 0, v[52:53]
	v_lshl_add_u64 v[52:53], v[52:53], 0, v[74:75]
	v_mul_f32_e32 v51, 0x45800000, v50
	v_cndmask_b32_e32 v50, v50, v51, vcc
	v_pk_fma_f32 v[48:49], v[48:49], v[50:51], v[72:73] op_sel_hi:[1,0,1]
	v_pk_fma_f32 v[46:47], v[46:47], v[50:51], v[70:71] op_sel_hi:[1,0,1]
	global_store_dwordx4 v[52:53], v[46:49], off
	v_pk_fma_f32 v[44:45], v[44:45], v[50:51], v[68:69] op_sel_hi:[1,0,1]
	v_pk_fma_f32 v[42:43], v[42:43], v[50:51], v[66:67] op_sel_hi:[1,0,1]
	v_add_u32_e32 v46, 48, v194
	v_ashrrev_i32_e32 v47, 31, v46
	global_store_dwordx4 v[52:53], v[42:45], off offset:16
	s_nop 1
	v_lshlrev_b64 v[42:43], 6, v[46:47]
	v_lshl_add_u64 v[42:43], s[68:69], 0, v[42:43]
	v_lshl_add_u64 v[42:43], v[42:43], 0, v[76:77]
	s_waitcnt vmcnt(10)
	v_mov_b32_e32 v42, v112
	v_mov_b32_e32 v43, v113
	v_mov_b32_e32 v44, v114
	v_mov_b32_e32 v45, v115
	v_add_f32_e32 v42, v42, v43
	v_add_f32_e32 v43, v44, v45
	v_add_f32_e32 v42, v42, v43
	v_mov_b32_e32 v43, v42
	s_nop 1
	v_permlane16_swap_b32_e32 v42, v43
	v_add_f32_e32 v42, v42, v43
	v_mov_b32_e32 v43, v42
	s_nop 1
	v_permlane32_swap_b32_e32 v42, v43
	v_add_f32_e32 v42, v42, v43
	v_fmamk_f32 v42, v42, 0x3a800000, v178
	v_cmp_gt_f32_e32 vcc, s84, v42
	v_mul_f32_e32 v43, 0x4b800000, v42
	v_lshlrev_b64 v[44:45], 7, v[46:47]
	v_cndmask_b32_e32 v42, v42, v43, vcc
	v_rsq_f32_e32 v42, v42
	v_lshl_add_u64 v[44:45], s[56:57], 0, v[44:45]
	v_lshl_add_u64 v[44:45], v[44:45], 0, v[74:75]
	v_mul_f32_e32 v43, 0x45800000, v42
	v_cndmask_b32_e32 v42, v42, v43, vcc
	v_pk_fma_f32 v[40:41], v[40:41], v[42:43], v[72:73] op_sel_hi:[1,0,1]
	v_pk_fma_f32 v[38:39], v[38:39], v[42:43], v[70:71] op_sel_hi:[1,0,1]
	global_store_dwordx4 v[44:45], v[38:41], off
	v_pk_fma_f32 v[36:37], v[36:37], v[42:43], v[68:69] op_sel_hi:[1,0,1]
	v_pk_fma_f32 v[34:35], v[34:35], v[42:43], v[66:67] op_sel_hi:[1,0,1]
	v_add_u32_e32 v38, 0x80, v194
	v_ashrrev_i32_e32 v39, 31, v38
	global_store_dwordx4 v[44:45], v[34:37], off offset:16
	s_nop 1
	v_lshlrev_b64 v[34:35], 6, v[38:39]
	v_lshl_add_u64 v[34:35], s[68:69], 0, v[34:35]
	v_lshl_add_u64 v[34:35], v[34:35], 0, v[76:77]
	s_waitcnt vmcnt(11)
	v_mov_b32_e32 v34, v120
	v_mov_b32_e32 v35, v121
	v_mov_b32_e32 v36, v122
	v_mov_b32_e32 v37, v123
	v_add_f32_e32 v34, v34, v35
	v_add_f32_e32 v35, v36, v37
	v_add_f32_e32 v34, v34, v35
	v_mov_b32_e32 v35, v34
	s_nop 1
	v_permlane16_swap_b32_e32 v34, v35
	v_add_f32_e32 v34, v34, v35
	v_mov_b32_e32 v35, v34
	s_nop 1
	v_permlane32_swap_b32_e32 v34, v35
	v_add_f32_e32 v34, v34, v35
	v_fmamk_f32 v34, v34, 0x3a800000, v178
	v_cmp_gt_f32_e32 vcc, s84, v34
	v_mul_f32_e32 v35, 0x4b800000, v34
	v_lshlrev_b64 v[36:37], 7, v[38:39]
	v_cndmask_b32_e32 v34, v34, v35, vcc
	v_rsq_f32_e32 v34, v34
	v_lshl_add_u64 v[36:37], s[56:57], 0, v[36:37]
	v_lshl_add_u64 v[36:37], v[36:37], 0, v[74:75]
	v_mul_f32_e32 v35, 0x45800000, v34
	v_cndmask_b32_e32 v34, v34, v35, vcc
	v_pk_fma_f32 v[32:33], v[32:33], v[34:35], v[72:73] op_sel_hi:[1,0,1]
	v_pk_fma_f32 v[30:31], v[30:31], v[34:35], v[70:71] op_sel_hi:[1,0,1]
	global_store_dwordx4 v[36:37], v[30:33], off
	v_pk_fma_f32 v[28:29], v[28:29], v[34:35], v[68:69] op_sel_hi:[1,0,1]
	v_pk_fma_f32 v[26:27], v[26:27], v[34:35], v[66:67] op_sel_hi:[1,0,1]
	v_add_u32_e32 v30, 0x90, v194
	v_ashrrev_i32_e32 v31, 31, v30
	global_store_dwordx4 v[36:37], v[26:29], off offset:16
	s_nop 1
	v_lshlrev_b64 v[26:27], 6, v[30:31]
	v_lshl_add_u64 v[26:27], s[68:69], 0, v[26:27]
	v_lshl_add_u64 v[26:27], v[26:27], 0, v[76:77]
	s_waitcnt vmcnt(12)
	v_mov_b32_e32 v26, v124
	v_mov_b32_e32 v27, v125
	v_mov_b32_e32 v28, v126
	v_mov_b32_e32 v29, v127
	v_add_f32_e32 v26, v26, v27
	v_add_f32_e32 v27, v28, v29
	v_add_f32_e32 v26, v26, v27
	v_mov_b32_e32 v27, v26
	s_nop 1
	v_permlane16_swap_b32_e32 v26, v27
	v_add_f32_e32 v26, v26, v27
	v_mov_b32_e32 v27, v26
	s_nop 1
	v_permlane32_swap_b32_e32 v26, v27
	v_add_f32_e32 v26, v26, v27
	v_fmamk_f32 v26, v26, 0x3a800000, v178
	v_cmp_gt_f32_e32 vcc, s84, v26
	v_mul_f32_e32 v27, 0x4b800000, v26
	v_lshlrev_b64 v[28:29], 7, v[30:31]
	v_cndmask_b32_e32 v26, v26, v27, vcc
	v_rsq_f32_e32 v26, v26
	v_lshl_add_u64 v[28:29], s[56:57], 0, v[28:29]
	v_lshl_add_u64 v[28:29], v[28:29], 0, v[74:75]
	v_mul_f32_e32 v27, 0x45800000, v26
	v_cndmask_b32_e32 v26, v26, v27, vcc
	v_pk_fma_f32 v[24:25], v[24:25], v[26:27], v[72:73] op_sel_hi:[1,0,1]
	v_pk_fma_f32 v[22:23], v[22:23], v[26:27], v[70:71] op_sel_hi:[1,0,1]
	global_store_dwordx4 v[28:29], v[22:25], off
	v_pk_fma_f32 v[20:21], v[20:21], v[26:27], v[68:69] op_sel_hi:[1,0,1]
	v_pk_fma_f32 v[18:19], v[18:19], v[26:27], v[66:67] op_sel_hi:[1,0,1]
	v_add_u32_e32 v22, 0xa0, v194
	v_ashrrev_i32_e32 v23, 31, v22
	global_store_dwordx4 v[28:29], v[18:21], off offset:16
	s_nop 1
	v_lshlrev_b64 v[18:19], 6, v[22:23]
	v_lshl_add_u64 v[18:19], s[68:69], 0, v[18:19]
	v_lshl_add_u64 v[18:19], v[18:19], 0, v[76:77]
	s_waitcnt vmcnt(13)
	v_mov_b32_e32 v18, v128
	v_mov_b32_e32 v19, v129
	v_mov_b32_e32 v20, v130
	v_mov_b32_e32 v21, v131
	v_add_f32_e32 v18, v18, v19
	v_add_f32_e32 v19, v20, v21
	v_add_f32_e32 v18, v18, v19
	v_mov_b32_e32 v19, v18
	s_nop 1
	v_permlane16_swap_b32_e32 v18, v19
	v_add_f32_e32 v18, v18, v19
	v_mov_b32_e32 v19, v18
	s_nop 1
	v_permlane32_swap_b32_e32 v18, v19
	v_add_f32_e32 v18, v18, v19
	v_fmamk_f32 v18, v18, 0x3a800000, v178
	v_cmp_gt_f32_e32 vcc, s84, v18
	v_mul_f32_e32 v19, 0x4b800000, v18
	v_lshlrev_b64 v[20:21], 7, v[22:23]
	v_cndmask_b32_e32 v18, v18, v19, vcc
	v_rsq_f32_e32 v18, v18
	v_lshl_add_u64 v[20:21], s[56:57], 0, v[20:21]
	v_lshl_add_u64 v[20:21], v[20:21], 0, v[74:75]
	v_mul_f32_e32 v19, 0x45800000, v18
	v_cndmask_b32_e32 v18, v18, v19, vcc
	v_pk_fma_f32 v[16:17], v[16:17], v[18:19], v[72:73] op_sel_hi:[1,0,1]
	v_pk_fma_f32 v[14:15], v[14:15], v[18:19], v[70:71] op_sel_hi:[1,0,1]
	global_store_dwordx4 v[20:21], v[14:17], off
	v_pk_fma_f32 v[12:13], v[12:13], v[18:19], v[68:69] op_sel_hi:[1,0,1]
	v_pk_fma_f32 v[10:11], v[10:11], v[18:19], v[66:67] op_sel_hi:[1,0,1]
	v_add_u32_e32 v14, 0xb0, v194
	v_ashrrev_i32_e32 v15, 31, v14
	global_store_dwordx4 v[20:21], v[10:13], off offset:16
	s_nop 1
	v_lshlrev_b64 v[10:11], 6, v[14:15]
	v_lshl_add_u64 v[10:11], s[68:69], 0, v[10:11]
	v_lshl_add_u64 v[10:11], v[10:11], 0, v[76:77]
	s_waitcnt vmcnt(14)
	v_mov_b32_e32 v10, v132
	v_mov_b32_e32 v11, v133
	v_mov_b32_e32 v12, v134
	v_mov_b32_e32 v13, v135
	v_add_f32_e32 v10, v10, v11
	v_add_f32_e32 v11, v12, v13
	v_add_f32_e32 v10, v10, v11
	v_mov_b32_e32 v11, v10
	s_nop 1
	v_permlane16_swap_b32_e32 v10, v11
	v_add_f32_e32 v10, v10, v11
	v_mov_b32_e32 v11, v10
	s_nop 1
	v_permlane32_swap_b32_e32 v10, v11
	v_add_f32_e32 v10, v10, v11
	v_fmamk_f32 v10, v10, 0x3a800000, v178
	v_cmp_gt_f32_e32 vcc, s84, v10
	v_mul_f32_e32 v11, 0x4b800000, v10
	v_lshlrev_b64 v[12:13], 7, v[14:15]
	v_cndmask_b32_e32 v10, v10, v11, vcc
	v_rsq_f32_e32 v10, v10
	v_lshl_add_u64 v[12:13], s[56:57], 0, v[12:13]
	v_lshl_add_u64 v[12:13], v[12:13], 0, v[74:75]
	v_mul_f32_e32 v11, 0x45800000, v10
	v_cndmask_b32_e32 v10, v10, v11, vcc
	v_pk_fma_f32 v[8:9], v[8:9], v[10:11], v[72:73] op_sel_hi:[1,0,1]
	v_pk_fma_f32 v[6:7], v[6:7], v[10:11], v[70:71] op_sel_hi:[1,0,1]
	v_pk_fma_f32 v[4:5], v[4:5], v[10:11], v[68:69] op_sel_hi:[1,0,1]
	v_pk_fma_f32 v[2:3], v[2:3], v[10:11], v[66:67] op_sel_hi:[1,0,1]
	global_store_dwordx4 v[12:13], v[6:9], off
	global_store_dwordx4 v[12:13], v[2:5], off offset:16
	s_andn2_b64 vcc, exec, s[6:7]
	s_mov_b64 s[6:7], -1
	s_cbranch_vccnz .LBB0_516
	s_branch .LBB0_682
